# U pass: x activations staged per column slice through LDS (2 coalesced loads per 16 steps instead of one replicated load per step); fused lshl_or address math
# speedup vs baseline: 1.0448x; 1.0113x over previous
.LBB0_922:
	v_lshl_add_u32 v176, s33, 7, v175
	v_ashrrev_i32_e32 v177, 31, v176
	v_lshrrev_b32_e32 v229, 2, v136
	v_and_b32_e32 v230, 7, v229
	v_lshrrev_b32_e32 v229, 3, v229
	v_add_u32_e32 v227, v176, v229
	v_lshlrev_b32_e32 v227, 11, v227
	v_lshl_or_b32 v227, v230, 4, v227
	v_lshlrev_b32_e32 v228, 7, v175
	v_add_u32_e32 v228, 0x20010, v228
	v_lshl_add_u32 v230, v230, 4, v228
	v_lshl_add_u32 v228, v136, 2, v228
	v_add_u32_e32 v233, 0x4000, v227
	global_load_dwordx4 v[218:221], v227, s[30:31]
	global_load_dwordx4 v[222:225], v233, s[30:31]
	v_lshlrev_b64 v[0:1], 9, v[176:177]
	v_lshl_add_u64 v[4:5], v[140:141], 0, v[0:1]
	global_load_dwordx4 v[0:3], v[4:5], off
	global_load_dwordx4 v[68:71], v[4:5], off offset:1024
	global_load_dwordx4 v[72:75], v[4:5], off offset:2048
	global_load_dwordx4 v[76:79], v[4:5], off offset:3072
	v_add_co_u32_e32 v4, vcc, s41, v4
	v_lshlrev_b64 v[6:7], 11, v[176:177]
	s_nop 0
	v_addc_co_u32_e32 v5, vcc, 0, v5, vcc
	global_load_dwordx4 v[80:83], v[4:5], off
	global_load_dwordx4 v[84:87], v[4:5], off offset:1024
	s_mov_b32 s59, 0x40000
	s_movk_i32 s61, 0x100
	s_mov_b32 s63, 16
	s_mov_b32 s0, s35
	s_waitcnt vmcnt(0)
	ds_write_b128 v188, v[0:3]
	ds_write_b128 v228, v[218:221]
	ds_write_b128 v228, v[222:225] offset:1024
	ds_read_b128 v[64:67], v230
	ds_read_b128 v[0:3], v189
	global_load_dwordx4 v[88:91], v[4:5], off offset:2048
	global_load_dwordx4 v[92:95], v[4:5], off offset:3072
	ds_read_b128 v[4:7], v189 offset:16
	ds_read_b128 v[8:11], v189 offset:32
	ds_read_b128 v[12:15], v189 offset:48
	s_waitcnt lgkmcnt(0)
	v_lshl_or_b32 v16, v1, 7, v137
	v_lshl_or_b32 v0, v0, 7, v174
	v_lshl_or_b32 v17, v3, 7, v137
	v_lshl_or_b32 v18, v2, 7, v174
	v_lshl_or_b32 v20, v5, 7, v137
	v_lshl_or_b32 v19, v4, 7, v174
	v_lshl_or_b32 v28, v7, 7, v137
	v_lshl_or_b32 v24, v6, 7, v174
	v_lshl_or_b32 v36, v9, 7, v137
	v_lshl_or_b32 v32, v8, 7, v174
	v_lshl_or_b32 v44, v11, 7, v137
	v_lshl_or_b32 v40, v10, 7, v174
	v_lshl_or_b32 v52, v13, 7, v137
	v_lshl_or_b32 v48, v12, 7, v174
	v_lshl_or_b32 v60, v15, 7, v137
	v_lshl_or_b32 v56, v14, 7, v174
	global_load_dwordx4 v[0:3], v0, s[36:37]
	s_nop 0
	global_load_dwordx4 v[4:7], v16, s[36:37]
	global_load_dwordx4 v[8:11], v18, s[36:37]
	global_load_dwordx4 v[12:15], v17, s[36:37]
	s_nop 0
	global_load_dwordx4 v[16:19], v19, s[36:37]
	s_nop 0
	global_load_dwordx4 v[20:23], v20, s[36:37]
	s_nop 0
	global_load_dwordx4 v[24:27], v24, s[36:37]
	s_nop 0
	global_load_dwordx4 v[28:31], v28, s[36:37]
	s_nop 0
	global_load_dwordx4 v[32:35], v32, s[36:37]
	s_nop 0
	global_load_dwordx4 v[36:39], v36, s[36:37]
	s_nop 0
	global_load_dwordx4 v[40:43], v40, s[36:37]
	s_nop 0
	global_load_dwordx4 v[44:47], v44, s[36:37]
	s_nop 0
	global_load_dwordx4 v[48:51], v48, s[36:37]
	s_nop 0
	global_load_dwordx4 v[52:55], v52, s[36:37]
	s_nop 0
	global_load_dwordx4 v[56:59], v56, s[36:37]
	s_nop 0
	global_load_dwordx4 v[60:63], v60, s[36:37]
	ds_write_b128 v194, v[68:71]
	ds_write_b128 v195, v[72:75]
	ds_write_b128 v196, v[76:79]
	ds_write_b128 v197, v[80:83]
	ds_write_b128 v198, v[84:87]
	s_waitcnt vmcnt(17)
	ds_write_b128 v199, v[88:91]
	s_waitcnt vmcnt(16)
	ds_write_b128 v200, v[92:95]
	s_branch .LBB0_924
.LBB0_923:
	s_add_i32 s63, s63, 16
	s_addk_i32 s61, 0x100
	s_add_i32 s59, s59, 0x40000
	s_andn2_b64 vcc, exec, s[0:1]
	s_mov_b32 s0, s67
	ds_write_b64 v70, v[68:69]
	s_and_b32 s98, s0, 14
	s_cmp_lg_u32 s98, 0
	s_cbranch_scc1 .Lux_skip2
	ds_write_b128 v228, v[218:221]
	ds_write_b128 v228, v[222:225] offset:1024
.Lux_skip2:
	s_and_b32 s98, s0, 15
	v_lshl_add_u32 v231, s98, 7, v230
	ds_read_b128 v[64:67], v231
	s_cbranch_vccz .LBB0_930
.LBB0_924:
	s_add_i32 s15, s61, 0xffffff80
	s_and_b32 s65, s15, 0x780
	s_add_i32 s14, s59, 0xfffc0000
	s_add_i32 s1, s0, 1
	s_and_b32 s14, s14, 0x1e00000
	s_add_u32 s14, s36, s14
	s_addc_u32 s15, s37, 0
	s_and_b32 s99, s1, 15
	s_lshl_b32 s99, s99, 7
	v_lshl_add_u32 v80, s65, 2, v189
	ds_read_b128 v[68:71], v80
	ds_read_b128 v[72:75], v80 offset:16
	ds_read_b128 v[76:79], v80 offset:32
	ds_read_b128 v[80:83], v80 offset:48
	s_waitcnt lgkmcnt(0)
	v_mov_b32_e32 v138, v139
	v_mov_b32_e32 v178, v139
	v_mov_b32_e32 v185, v139
	v_mov_b32_e32 v186, v139
	s_waitcnt vmcnt(0)
	s_and_b32 s98, s0, 14
	s_cmp_lg_u32 s98, 14
	s_cbranch_scc1 .Lux_skip1
	s_add_i32 s98, s0, 2
	s_lshr_b32 s98, s98, 4
	s_lshl_b32 s98, s98, 7
	v_add_u32_e32 v232, s98, v227
	v_add_u32_e32 v233, 0x4000, v232
	global_load_dwordx4 v[218:221], v232, s[30:31]
	global_load_dwordx4 v[222:225], v233, s[30:31]
.Lux_skip1:
	v_dot4c_i32_i8_e32 v138, v0, v64
	v_dot4c_i32_i8_e32 v178, v4, v64
	v_dot4c_i32_i8_e32 v185, v32, v64
	v_dot4c_i32_i8_e32 v186, v36, v64
	v_dot4c_i32_i8_e32 v138, v1, v65
	v_lshl_or_b32 v69, v69, 7, v137
	v_lshl_or_b32 v68, v68, 7, v174
	global_load_dwordx4 v[132:135], v68, s[14:15]
	global_load_dwordx4 v[128:131], v69, s[14:15]
	v_dot4c_i32_i8_e32 v178, v5, v65
	v_dot4c_i32_i8_e32 v185, v33, v65
	v_dot4c_i32_i8_e32 v186, v37, v65
	v_dot4c_i32_i8_e32 v138, v2, v66
	v_dot4c_i32_i8_e32 v178, v6, v66
	v_dot4c_i32_i8_e32 v185, v34, v66
	v_dot4c_i32_i8_e32 v186, v38, v66
	v_dot4c_i32_i8_e32 v138, v3, v67
	v_dot4c_i32_i8_e32 v178, v7, v67
	v_dot4c_i32_i8_e32 v185, v35, v67
	v_dot4c_i32_i8_e32 v186, v39, v67
	v_mov_b32_e32 v180, v139
	v_lshl_or_b32 v69, v70, 7, v174
	v_lshl_or_b32 v68, v71, 7, v137
	global_load_dwordx4 v[124:127], v69, s[14:15]
	global_load_dwordx4 v[120:123], v68, s[14:15]
	v_mov_b32_e32 v210, v139
	v_cndmask_b32_e64 v215, v185, v138, s[2:3]
	v_cndmask_b32_e64 v138, v138, v185, s[2:3]
	v_cndmask_b32_e64 v185, v178, v186, s[2:3]
	ds_bpermute_b32 v185, v201, v185
	v_dot4c_i32_i8_e32 v180, v12, v64
	v_mov_b32_e32 v181, v139
	v_dot4c_i32_i8_e32 v210, v44, v64
	v_mov_b32_e32 v211, v139
	v_dot4c_i32_i8_e32 v180, v13, v65
	v_dot4c_i32_i8_e32 v181, v16, v64
	v_lshl_or_b32 v69, v72, 7, v174
	v_lshl_or_b32 v68, v73, 7, v137
	global_load_dwordx4 v[116:119], v69, s[14:15]
	global_load_dwordx4 v[112:115], v68, s[14:15]
	v_dot4c_i32_i8_e32 v210, v45, v65
	v_dot4c_i32_i8_e32 v211, v48, v64
	v_dot4c_i32_i8_e32 v180, v14, v66
	v_dot4c_i32_i8_e32 v181, v17, v65
	v_dot4c_i32_i8_e32 v210, v46, v66
	v_dot4c_i32_i8_e32 v211, v49, v65
	v_dot4c_i32_i8_e32 v180, v15, v67
	v_dot4c_i32_i8_e32 v181, v18, v66
	v_dot4c_i32_i8_e32 v210, v47, v67
	v_dot4c_i32_i8_e32 v211, v50, v66
	v_cndmask_b32_e64 v178, v186, v178, s[2:3]
	v_lshl_or_b32 v69, v74, 7, v174
	v_lshl_or_b32 v68, v75, 7, v137
	global_load_dwordx4 v[108:111], v69, s[14:15]
	global_load_dwordx4 v[104:107], v68, s[14:15]
	v_mov_b32_e32 v179, v139
	v_dot4c_i32_i8_e32 v181, v19, v67
	v_mov_b32_e32 v182, v139
	v_mov_b32_e32 v187, v139
	v_dot4c_i32_i8_e32 v211, v51, v67
	v_mov_b32_e32 v212, v139
	s_waitcnt lgkmcnt(0)
	v_add_u32_e32 v178, v185, v178
	v_cndmask_b32_e64 v185, v210, v180, s[2:3]
	v_cndmask_b32_e64 v180, v180, v210, s[2:3]
	v_dot4c_i32_i8_e32 v179, v8, v64
	v_dot4c_i32_i8_e32 v182, v20, v64
	v_lshl_or_b32 v69, v76, 7, v174
	v_lshl_or_b32 v68, v77, 7, v137
	global_load_dwordx4 v[100:103], v69, s[14:15]
	global_load_dwordx4 v[96:99], v68, s[14:15]
	v_mov_b32_e32 v183, v139
	v_dot4c_i32_i8_e32 v187, v40, v64
	v_dot4c_i32_i8_e32 v212, v52, v64
	v_mov_b32_e32 v213, v139
	ds_bpermute_b32 v180, v201, v180
	v_cndmask_b32_e64 v186, v181, v211, s[2:3]
	v_dot4c_i32_i8_e32 v179, v9, v65
	v_dot4c_i32_i8_e32 v182, v21, v65
	v_dot4c_i32_i8_e32 v183, v24, v64
	v_mov_b32_e32 v184, v139
	v_dot4c_i32_i8_e32 v187, v41, v65
	v_lshl_or_b32 v69, v78, 7, v174
	v_lshl_or_b32 v68, v79, 7, v137
	global_load_dwordx4 v[92:95], v69, s[14:15]
	global_load_dwordx4 v[88:91], v68, s[14:15]
	v_dot4c_i32_i8_e32 v212, v53, v65
	v_dot4c_i32_i8_e32 v213, v56, v64
	v_mov_b32_e32 v214, v139
	ds_bpermute_b32 v186, v201, v186
	v_dot4c_i32_i8_e32 v179, v10, v66
	v_dot4c_i32_i8_e32 v182, v22, v66
	v_dot4c_i32_i8_e32 v183, v25, v65
	v_dot4c_i32_i8_e32 v184, v28, v64
	v_dot4c_i32_i8_e32 v187, v42, v66
	v_dot4c_i32_i8_e32 v212, v54, v66
	v_dot4c_i32_i8_e32 v213, v57, v65
	v_lshlrev_b32_e32 v69, 7, v80
	v_lshlrev_b32_e32 v68, 7, v81
	v_or_b32_e32 v68, v68, v137
	v_or_b32_e32 v69, v69, v174
	global_load_dwordx4 v[84:87], v69, s[14:15]
	global_load_dwordx4 v[76:79], v68, s[14:15]
	v_dot4c_i32_i8_e32 v214, v60, v64
	v_dot4c_i32_i8_e32 v179, v11, v67
	v_dot4c_i32_i8_e32 v182, v23, v67
	v_dot4c_i32_i8_e32 v183, v26, v66
	v_dot4c_i32_i8_e32 v184, v29, v65
	v_dot4c_i32_i8_e32 v187, v43, v67
	v_dot4c_i32_i8_e32 v212, v55, v67
	v_dot4c_i32_i8_e32 v213, v58, v66
	v_dot4c_i32_i8_e32 v214, v61, v65
	v_dot4c_i32_i8_e32 v183, v27, v67
	v_dot4c_i32_i8_e32 v184, v30, v66
	v_dot4c_i32_i8_e32 v213, v59, v67
	v_lshl_or_b32 v68, v83, 7, v137
	v_lshl_or_b32 v69, v82, 7, v174
	global_load_dwordx4 v[72:75], v69, s[14:15]
	global_load_dwordx4 v[68:71], v68, s[14:15]
	v_add_u32_e32 v231, s99, v230
	ds_read_b128 v[80:83], v231
	v_dot4c_i32_i8_e32 v214, v62, v66
	v_cndmask_b32_e64 v216, v179, v187, s[2:3]
	v_cndmask_b32_e64 v179, v187, v179, s[2:3]
	v_cndmask_b32_e64 v187, v182, v212, s[2:3]
	v_dot4c_i32_i8_e32 v184, v31, v67
	v_dot4c_i32_i8_e32 v214, v63, v67
	ds_bpermute_b32 v138, v201, v138
	ds_bpermute_b32 v187, v201, v187
	s_waitcnt lgkmcnt(3)
	v_add_u32_e32 v180, v180, v185
	v_cndmask_b32_e64 v181, v211, v181, s[2:3]
	v_cndmask_b32_e64 v185, v213, v183, s[2:3]
	v_cndmask_b32_e64 v183, v183, v213, s[2:3]
	ds_bpermute_b32 v216, v201, v216
	s_waitcnt lgkmcnt(3)
	v_add_u32_e32 v181, v186, v181
	ds_bpermute_b32 v183, v201, v183
	v_cndmask_b32_e64 v186, v184, v214, s[2:3]
	ds_bpermute_b32 v186, v201, v186
	v_cndmask_b32_e64 v182, v212, v182, s[2:3]
	s_waitcnt lgkmcnt(4)
	v_add_u32_e32 v138, v138, v215
	s_waitcnt lgkmcnt(3)
	v_add_u32_e32 v182, v187, v182
	s_waitcnt lgkmcnt(2)
	v_add_u32_e32 v179, v216, v179
	v_cndmask_b32_e64 v187, v138, v181, s[4:5]
	s_waitcnt lgkmcnt(1)
	v_add_u32_e32 v183, v183, v185
	v_cndmask_b32_e64 v184, v214, v184, s[2:3]
	v_cndmask_b32_e64 v138, v181, v138, s[4:5]
	v_cndmask_b32_e64 v181, v182, v178, s[4:5]
	v_cndmask_b32_e64 v178, v178, v182, s[4:5]
	s_waitcnt lgkmcnt(0)
	v_add_u32_e32 v184, v186, v184
	ds_bpermute_b32 v178, v202, v178
	v_cndmask_b32_e64 v182, v179, v183, s[4:5]
	ds_bpermute_b32 v187, v202, v187
	ds_bpermute_b32 v182, v202, v182
	v_cndmask_b32_e64 v185, v180, v184, s[4:5]
	ds_bpermute_b32 v185, v202, v185
	s_waitcnt lgkmcnt(3)
	v_add_u32_e32 v181, v178, v181
	v_cndmask_b32_e64 v178, v183, v179, s[4:5]
	s_waitcnt lgkmcnt(2)
	v_add_u32_e32 v138, v187, v138
	s_waitcnt lgkmcnt(1)
	v_add_u32_e32 v178, v182, v178
	v_cndmask_b32_e64 v179, v184, v180, s[4:5]
	s_waitcnt lgkmcnt(0)
	v_add_u32_e32 v179, v185, v179
	v_cndmask_b32_e64 v180, v138, v178, s[6:7]
	ds_bpermute_b32 v180, v203, v180
	v_cndmask_b32_e64 v182, v181, v179, s[6:7]
	ds_bpermute_b32 v182, v203, v182
	s_add_i32 s1, s61, 0xffffff00
	v_cndmask_b32_e64 v138, v178, v138, s[6:7]
	s_and_b32 s1, s1, 0x700
	s_waitcnt lgkmcnt(1)
	v_add_u32_e32 v178, v180, v138
	v_cndmask_b32_e64 v138, v179, v181, s[6:7]
	s_cmp_gt_u32 s0, 15
	s_waitcnt lgkmcnt(0)
	v_add_u32_e32 v179, v182, v138
	s_cselect_b64 s[14:15], -1, 0
	s_cmp_lt_u32 s0, 16
	v_lshl_add_u32 v138, s1, 2, v190
	s_cbranch_scc1 .LBB0_926
	ds_read_b64 v[180:181], v138
	s_waitcnt lgkmcnt(0)
	v_add_u32_e32 v178, v180, v178
	v_add_u32_e32 v179, v181, v179
.LBB0_926:
	s_add_i32 s67, s0, 2
	s_cmpk_gt_u32 s0, 0xfd
	s_cselect_b64 s[0:1], -1, 0
	s_and_b64 vcc, exec, s[0:1]
	ds_write_b64 v138, v[178:179]
	s_and_b32 s17, s61, 0x700
	v_lshl_add_u32 v0, s17, 2, v189
	ds_read_b128 v[6:9], v0
	ds_read_b128 v[22:25], v0 offset:16
	ds_read_b128 v[38:41], v0 offset:32
	ds_read_b128 v[54:57], v0 offset:48
	s_and_b32 s16, s59, 0x3e00000
	s_add_u32 s16, s36, s16
	s_addc_u32 s17, s37, 0
	s_waitcnt lgkmcnt(3)
	s_waitcnt lgkmcnt(2)
	s_waitcnt lgkmcnt(1)
	s_waitcnt lgkmcnt(0)
	v_lshl_or_b32 v4, v7, 7, v137
	v_lshl_or_b32 v0, v6, 7, v174
	v_lshl_or_b32 v12, v9, 7, v137
	v_lshl_or_b32 v8, v8, 7, v174
	v_lshl_or_b32 v20, v23, 7, v137
	v_lshl_or_b32 v16, v22, 7, v174
	v_lshl_or_b32 v28, v25, 7, v137
	v_lshl_or_b32 v24, v24, 7, v174
	v_lshl_or_b32 v36, v39, 7, v137
	v_lshl_or_b32 v32, v38, 7, v174
	v_lshl_or_b32 v44, v41, 7, v137
	v_lshl_or_b32 v40, v40, 7, v174
	v_lshl_or_b32 v52, v55, 7, v137
	v_lshl_or_b32 v48, v54, 7, v174
	v_lshl_or_b32 v60, v57, 7, v137
	v_lshl_or_b32 v56, v56, 7, v174
.LBB0_928:
	v_mov_b32_e32 v138, v139
	s_waitcnt vmcnt(0)
	v_dot4c_i32_i8_e32 v138, v132, v80
	v_mov_b32_e32 v132, v139
	global_load_dwordx4 v[0:3], v0, s[16:17]
	v_dot4c_i32_i8_e32 v132, v128, v80
	v_mov_b32_e32 v128, v139
	v_dot4c_i32_i8_e32 v128, v124, v80
	v_mov_b32_e32 v124, v139
	v_dot4c_i32_i8_e32 v124, v120, v80
	global_load_dwordx4 v[4:7], v4, s[16:17]
	v_mov_b32_e32 v120, v139
	v_dot4c_i32_i8_e32 v120, v116, v80
	v_mov_b32_e32 v116, v139
	v_dot4c_i32_i8_e32 v116, v112, v80
	v_mov_b32_e32 v112, v139
	global_load_dwordx4 v[8:11], v8, s[16:17]
	v_dot4c_i32_i8_e32 v112, v108, v80
	v_mov_b32_e32 v108, v139
	v_dot4c_i32_i8_e32 v108, v104, v80
	v_mov_b32_e32 v104, v139
	v_dot4c_i32_i8_e32 v104, v100, v80
	global_load_dwordx4 v[12:15], v12, s[16:17]
	v_mov_b32_e32 v100, v139
	v_dot4c_i32_i8_e32 v100, v96, v80
	v_mov_b32_e32 v96, v139
	v_dot4c_i32_i8_e32 v96, v92, v80
	v_mov_b32_e32 v92, v139
	v_dot4c_i32_i8_e32 v92, v88, v80
	global_load_dwordx4 v[16:19], v16, s[16:17]
	v_mov_b32_e32 v88, v139
	v_dot4c_i32_i8_e32 v88, v84, v80
	v_mov_b32_e32 v84, v139
	v_dot4c_i32_i8_e32 v138, v133, v81
	v_dot4c_i32_i8_e32 v104, v101, v81
	global_load_dwordx4 v[20:23], v20, s[16:17]
	v_dot4c_i32_i8_e32 v84, v76, v80
	v_mov_b32_e32 v76, v139
	v_dot4c_i32_i8_e32 v138, v134, v82
	v_dot4c_i32_i8_e32 v132, v129, v81
	v_dot4c_i32_i8_e32 v104, v102, v82
	global_load_dwordx4 v[24:27], v24, s[16:17]
	v_dot4c_i32_i8_e32 v100, v97, v81
	v_dot4c_i32_i8_e32 v76, v72, v80
	v_mov_b32_e32 v72, v139
	v_dot4c_i32_i8_e32 v138, v135, v83
	v_dot4c_i32_i8_e32 v132, v130, v82
	global_load_dwordx4 v[28:31], v28, s[16:17]
	v_dot4c_i32_i8_e32 v128, v125, v81
	v_dot4c_i32_i8_e32 v104, v103, v83
	v_dot4c_i32_i8_e32 v100, v98, v82
	v_dot4c_i32_i8_e32 v96, v93, v81
	v_dot4c_i32_i8_e32 v72, v68, v80
	global_load_dwordx4 v[32:35], v32, s[16:17]
	v_dot4c_i32_i8_e32 v132, v131, v83
	v_dot4c_i32_i8_e32 v128, v126, v82
	v_dot4c_i32_i8_e32 v124, v121, v81
	v_dot4c_i32_i8_e32 v100, v99, v83
	v_dot4c_i32_i8_e32 v96, v94, v82
	global_load_dwordx4 v[36:39], v36, s[16:17]
	v_dot4c_i32_i8_e32 v92, v89, v81
	v_dot4c_i32_i8_e32 v72, v69, v81
	v_cndmask_b32_e64 v69, v138, v104, s[2:3]
	v_dot4c_i32_i8_e32 v128, v127, v83
	v_dot4c_i32_i8_e32 v124, v122, v82
	global_load_dwordx4 v[40:43], v40, s[16:17]
	v_dot4c_i32_i8_e32 v120, v117, v81
	v_dot4c_i32_i8_e32 v96, v95, v83
	v_dot4c_i32_i8_e32 v92, v90, v82
	v_dot4c_i32_i8_e32 v88, v85, v81
	v_dot4c_i32_i8_e32 v72, v70, v82
	global_load_dwordx4 v[44:47], v44, s[16:17]
	ds_bpermute_b32 v69, v201, v69
	v_cndmask_b32_e64 v70, v132, v100, s[2:3]
	v_dot4c_i32_i8_e32 v124, v123, v83
	v_dot4c_i32_i8_e32 v120, v118, v82
	v_dot4c_i32_i8_e32 v116, v113, v81
	global_load_dwordx4 v[48:51], v48, s[16:17]
	v_dot4c_i32_i8_e32 v92, v91, v83
	v_dot4c_i32_i8_e32 v88, v86, v82
	v_dot4c_i32_i8_e32 v84, v77, v81
	v_dot4c_i32_i8_e32 v72, v71, v83
	ds_bpermute_b32 v70, v201, v70
	v_cndmask_b32_e64 v71, v128, v96, s[2:3]
	global_load_dwordx4 v[52:55], v52, s[16:17]
	v_dot4c_i32_i8_e32 v120, v119, v83
	v_dot4c_i32_i8_e32 v116, v114, v82
	v_dot4c_i32_i8_e32 v88, v87, v83
	v_dot4c_i32_i8_e32 v84, v78, v82
	v_dot4c_i32_i8_e32 v76, v73, v81
	global_load_dwordx4 v[56:59], v56, s[16:17]
	ds_bpermute_b32 v71, v201, v71
	v_cndmask_b32_e64 v73, v124, v92, s[2:3]
	v_dot4c_i32_i8_e32 v116, v115, v83
	v_dot4c_i32_i8_e32 v84, v79, v83
	v_dot4c_i32_i8_e32 v76, v74, v82
	global_load_dwordx4 v[60:63], v60, s[16:17]
	ds_bpermute_b32 v73, v201, v73
	v_cndmask_b32_e64 v74, v120, v88, s[2:3]
	v_dot4c_i32_i8_e32 v76, v75, v83
	v_cndmask_b32_e64 v68, v104, v138, s[2:3]
	ds_bpermute_b32 v74, v201, v74
	v_cndmask_b32_e64 v75, v116, v84, s[2:3]
	s_waitcnt lgkmcnt(4)
	v_add_u32_e32 v68, v69, v68
	v_cndmask_b32_e64 v69, v100, v132, s[2:3]
	ds_bpermute_b32 v75, v201, v75
	s_waitcnt lgkmcnt(4)
	v_add_u32_e32 v69, v70, v69
	v_cndmask_b32_e64 v70, v96, v128, s[2:3]
	v_dot4c_i32_i8_e32 v112, v109, v81
	v_dot4c_i32_i8_e32 v108, v105, v81
	s_waitcnt lgkmcnt(3)
	v_add_u32_e32 v70, v71, v70
	v_cndmask_b32_e64 v71, v92, v124, s[2:3]
	v_dot4c_i32_i8_e32 v112, v110, v82
	v_dot4c_i32_i8_e32 v108, v106, v82
	s_waitcnt lgkmcnt(2)
	v_add_u32_e32 v71, v73, v71
	v_cndmask_b32_e64 v73, v88, v120, s[2:3]
	v_dot4c_i32_i8_e32 v112, v111, v83
	v_dot4c_i32_i8_e32 v108, v107, v83
	s_waitcnt lgkmcnt(1)
	v_add_u32_e32 v73, v74, v73
	v_cndmask_b32_e64 v74, v84, v116, s[2:3]
	s_waitcnt lgkmcnt(0)
	v_add_u32_e32 v74, v75, v74
	v_cndmask_b32_e64 v75, v76, v112, s[2:3]
	v_cndmask_b32_e64 v76, v112, v76, s[2:3]
	v_cndmask_b32_e64 v77, v108, v72, s[2:3]
	ds_bpermute_b32 v76, v201, v76
	ds_bpermute_b32 v77, v201, v77
	v_cndmask_b32_e64 v72, v72, v108, s[2:3]
	v_cndmask_b32_e64 v78, v68, v73, s[4:5]
	v_cndmask_b32_e64 v68, v73, v68, s[4:5]
	s_waitcnt lgkmcnt(1)
	v_add_u32_e32 v75, v76, v75
	s_waitcnt lgkmcnt(0)
	v_add_u32_e32 v72, v77, v72
	v_cndmask_b32_e64 v73, v74, v69, s[4:5]
	v_cndmask_b32_e64 v69, v69, v74, s[4:5]
	v_cndmask_b32_e64 v74, v70, v75, s[4:5]
	v_cndmask_b32_e64 v76, v71, v72, s[4:5]
	ds_bpermute_b32 v78, v202, v78
	ds_bpermute_b32 v69, v202, v69
	ds_bpermute_b32 v74, v202, v74
	ds_bpermute_b32 v76, v202, v76
	v_cndmask_b32_e64 v70, v75, v70, s[4:5]
	v_cndmask_b32_e64 v71, v72, v71, s[4:5]
	s_waitcnt lgkmcnt(3)
	v_add_u32_e32 v68, v78, v68
	s_waitcnt lgkmcnt(2)
	v_add_u32_e32 v69, v69, v73
	s_waitcnt lgkmcnt(1)
	v_add_u32_e32 v70, v74, v70
	s_waitcnt lgkmcnt(0)
	v_add_u32_e32 v71, v76, v71
	v_cndmask_b32_e64 v72, v68, v70, s[6:7]
	v_cndmask_b32_e64 v73, v69, v71, s[6:7]
	ds_bpermute_b32 v72, v203, v72
	ds_bpermute_b32 v73, v203, v73
	v_cndmask_b32_e64 v68, v70, v68, s[6:7]
	v_cndmask_b32_e64 v69, v71, v69, s[6:7]
	s_andn2_b64 vcc, exec, s[14:15]
	s_waitcnt lgkmcnt(1)
	v_add_u32_e32 v68, v72, v68
	s_waitcnt lgkmcnt(0)
	v_add_u32_e32 v69, v73, v69
	v_lshl_add_u32 v70, s65, 2, v190
	s_cbranch_vccnz .LBB0_923
	ds_read_b64 v[72:73], v70
	s_waitcnt lgkmcnt(0)
	v_add_u32_e32 v68, v72, v68
	v_add_u32_e32 v69, v73, v69
	s_branch .LBB0_923

.LBB0_931:
	s_lshl_b32 s0, s59, 9
	s_lshl_b32 s1, s34, 9
	v_add_u32_e32 v10, s0, v191
	v_add_u32_e32 v12, s1, v191
	v_add_u32_e32 v32, s0, v190
	v_add_u32_e32 v33, s1, v190
	ds_read_b64 v[10:11], v10
	ds_read_b64 v[12:13], v12
	ds_read_b64 v[16:17], v32
	ds_read_b64 v[18:19], v33
	v_or_b32_e32 v2, s34, v1
	v_or_b32_e32 v4, s59, v0
	v_ashrrev_i32_e32 v5, 31, v4
	v_ashrrev_i32_e32 v3, 31, v2
	v_lshlrev_b64 v[2:3], 9, v[2:3]
	v_lshlrev_b64 v[14:15], 9, v[4:5]
	v_lshl_add_u64 v[4:5], v[4:5], 2, s[24:25]
	v_lshl_add_u64 v[14:15], v[146:147], 0, v[14:15]
	v_lshl_add_u64 v[2:3], v[146:147], 0, v[2:3]
	s_waitcnt lgkmcnt(0)
	v_cvt_f32_i32_e32 v21, v18
	v_cvt_f32_i32_e32 v20, v16
	v_ashrrev_i32_e32 v23, 31, v12
	v_mov_b32_e32 v22, v12
	v_ashrrev_i32_e32 v25, 31, v10
	v_mov_b32_e32 v24, v10
	v_cvt_f32_i32_e32 v18, v17
	v_ashrrev_i32_e32 v17, 31, v13
	v_mov_b32_e32 v16, v13
	v_ashrrev_i32_e32 v13, 31, v11
	v_mov_b32_e32 v12, v11
	global_load_dwordx2 v[4:5], v[4:5], off
	s_nop 0
	global_load_dwordx2 v[14:15], v[14:15], off
	s_nop 0
	global_load_dwordx2 v[2:3], v[2:3], off
	v_lshlrev_b64 v[10:11], 2, v[24:25]
	v_lshlrev_b64 v[22:23], 2, v[22:23]
	v_lshlrev_b64 v[12:13], 2, v[12:13]
	v_lshlrev_b64 v[16:17], 2, v[16:17]
	v_lshl_add_u64 v[24:25], s[20:21], 0, v[10:11]
	v_lshl_add_u64 v[26:27], s[20:21], 0, v[22:23]
	v_lshl_add_u64 v[28:29], s[20:21], 0, v[12:13]
	v_lshl_add_u64 v[10:11], s[22:23], 0, v[10:11]
	v_lshl_add_u64 v[12:13], s[22:23], 0, v[12:13]
	v_lshl_add_u64 v[30:31], s[20:21], 0, v[16:17]
	v_lshl_add_u64 v[22:23], s[22:23], 0, v[22:23]
	v_lshl_add_u64 v[16:17], s[22:23], 0, v[16:17]
	global_load_dword v24, v[24:25], off
	s_nop 0
	global_load_dword v25, v[26:27], off
	s_nop 0
	global_load_dword v26, v[28:29], off
	global_load_dword v27, v[30:31], off
	s_nop 0
	global_load_dword v10, v[10:11], off
	s_nop 0
	global_load_dword v11, v[22:23], off
	s_nop 0
	global_load_dword v12, v[12:13], off
	s_nop 0
	global_load_dword v13, v[16:17], off
	v_cvt_f32_i32_e32 v19, v19
	v_mov_b64_e32 v[6:7], s[44:45]
	v_mov_b64_e32 v[8:9], s[62:63]
	s_add_i32 s59, s59, 2
	s_add_i32 s61, s61, -2
	s_add_i32 s34, s34, 2
	s_cmp_lg_u32 s61, 0
	s_waitcnt vmcnt(9)
	v_mov_b32_e32 v16, v14
	s_waitcnt vmcnt(8)
	v_mov_b32_e32 v17, v2
	v_mov_b32_e32 v2, v15
	s_waitcnt vmcnt(6)
	v_pk_mul_f32 v[14:15], v[4:5], v[24:25]
	s_waitcnt vmcnt(4)
	v_pk_mul_f32 v[4:5], v[4:5], v[26:27]
	s_nop 0
	v_pk_mul_f32 v[4:5], v[4:5], v[18:19]
	s_waitcnt vmcnt(2)
	v_pk_mul_f32 v[10:11], v[16:17], v[10:11]
	s_waitcnt vmcnt(0)
	v_pk_mul_f32 v[2:3], v[2:3], v[12:13]
	v_pk_mul_f32 v[12:13], v[14:15], v[20:21]
	v_pk_mul_f32 v[10:11], v[10:11], 0.5 op_sel_hi:[1,0]
	v_pk_mul_f32 v[2:3], v[2:3], 0.5 op_sel_hi:[1,0]
	v_pk_mul_f32 v[10:11], v[12:13], v[10:11]
	v_pk_mul_f32 v[12:13], v[12:13], s[40:41] op_sel_hi:[1,0]
	v_pk_mul_f32 v[2:3], v[4:5], v[2:3]
	v_pk_mul_f32 v[4:5], v[4:5], s[40:41] op_sel_hi:[1,0]
	v_and_b32_e32 v15, 0x7fffffff, v13
	v_and_b32_e32 v14, 0x7fffffff, v12
	v_pk_mul_f32 v[16:17], v[12:13], v[12:13]
	v_and_b32_e32 v19, 0x7fffffff, v5
	v_and_b32_e32 v18, 0x7fffffff, v4
	v_pk_mul_f32 v[20:21], v[4:5], v[4:5]
	v_pk_fma_f32 v[22:23], v[14:15], s[50:51], v[6:7] op_sel_hi:[1,0,0]
	v_pk_fma_f32 v[24:25], v[16:17], s[64:65], v[8:9] op_sel_hi:[1,0,0]
	v_pk_fma_f32 v[6:7], v[18:19], s[50:51], v[6:7] op_sel_hi:[1,0,0]
	v_pk_fma_f32 v[8:9], v[20:21], s[64:65], v[8:9] op_sel_hi:[1,0,0]
	v_pk_fma_f32 v[22:23], v[14:15], v[22:23], s[52:53] op_sel_hi:[1,1,0]
	v_pk_fma_f32 v[24:25], v[16:17], v[24:25], s[66:67] op_sel_hi:[1,1,0]
	v_pk_fma_f32 v[6:7], v[18:19], v[6:7], s[52:53] op_sel_hi:[1,1,0]
	v_pk_fma_f32 v[8:9], v[20:21], v[8:9], s[66:67] op_sel_hi:[1,1,0]
	v_pk_fma_f32 v[22:23], v[14:15], v[22:23], s[54:55] op_sel_hi:[1,1,0]
	v_pk_fma_f32 v[24:25], v[16:17], v[24:25], s[68:69] op_sel_hi:[1,1,0]
	v_pk_fma_f32 v[6:7], v[18:19], v[6:7], s[54:55] op_sel_hi:[1,1,0]
	v_pk_fma_f32 v[8:9], v[20:21], v[8:9], s[68:69] op_sel_hi:[1,1,0]
	v_pk_fma_f32 v[22:23], v[14:15], v[22:23], s[56:57] op_sel_hi:[1,1,0]
	v_pk_fma_f32 v[24:25], v[16:17], v[24:25], s[70:71] op_sel_hi:[1,1,0]
	v_pk_fma_f32 v[6:7], v[18:19], v[6:7], s[56:57] op_sel_hi:[1,1,0]
	v_pk_fma_f32 v[8:9], v[20:21], v[8:9], s[70:71] op_sel_hi:[1,1,0]
	v_pk_fma_f32 v[22:23], v[14:15], v[22:23], s[58:59] op_sel_hi:[1,1,0]
	v_pk_fma_f32 v[16:17], v[16:17], v[24:25], s[72:73] op_sel_hi:[1,1,0]
	v_pk_fma_f32 v[6:7], v[18:19], v[6:7], s[58:59] op_sel_hi:[1,1,0]
	v_pk_fma_f32 v[8:9], v[20:21], v[8:9], s[72:73] op_sel_hi:[1,1,0]
	v_pk_fma_f32 v[20:21], v[14:15], v[22:23], s[60:61] op_sel_hi:[1,1,0]
	v_pk_fma_f32 v[16:17], v[14:15], v[16:17], v[14:15]
	v_pk_fma_f32 v[6:7], v[18:19], v[6:7], s[60:61] op_sel_hi:[1,1,0]
	v_pk_fma_f32 v[14:15], v[14:15], v[20:21], v[14:15]
	v_pk_fma_f32 v[8:9], v[18:19], v[8:9], v[18:19]
	v_pk_fma_f32 v[6:7], v[18:19], v[6:7], v[18:19]
	v_mul_f32_e32 v18, 0xbfb8aa3b, v15
	v_mul_f32_e32 v19, 0xbfb8aa3b, v14
	v_mul_f32_e32 v20, 0xbfb8aa3b, v7
	v_mul_f32_e32 v21, 0xbfb8aa3b, v6
	v_fma_f32 v22, v15, s45, -v18
	v_rndne_f32_e32 v23, v18
	v_fma_f32 v24, v14, s45, -v19
	v_rndne_f32_e32 v25, v19
	v_fma_f32 v26, v7, s45, -v20
	v_rndne_f32_e32 v27, v20
	v_fma_f32 v28, v6, s45, -v21
	v_rndne_f32_e32 v29, v21
	v_fmac_f32_e32 v22, 0xb2a5705f, v15
	v_sub_f32_e32 v18, v18, v23
	v_fmac_f32_e32 v24, 0xb2a5705f, v14
	v_sub_f32_e32 v19, v19, v25
	v_fmac_f32_e32 v26, 0xb2a5705f, v7
	v_sub_f32_e32 v20, v20, v27
	v_fmac_f32_e32 v28, 0xb2a5705f, v6
	v_sub_f32_e32 v21, v21, v29
	v_add_f32_e32 v18, v18, v22
	v_add_f32_e32 v19, v19, v24
	v_cvt_i32_f32_e32 v23, v23
	v_cvt_i32_f32_e32 v25, v25
	v_add_f32_e32 v20, v20, v26
	v_add_f32_e32 v21, v21, v28
	v_exp_f32_e32 v18, v18
	v_exp_f32_e32 v19, v19
	v_cvt_i32_f32_e32 v27, v27
	v_cvt_i32_f32_e32 v29, v29
	v_exp_f32_e32 v20, v20
	v_exp_f32_e32 v21, v21
	v_ldexp_f32 v18, v18, v23
	v_ldexp_f32 v19, v19, v25
	v_cmp_nlt_f32_e32 vcc, s51, v14
	v_cmp_nlt_f32_e64 s[16:17], s51, v15
	v_ldexp_f32 v20, v20, v27
	v_cmp_nlt_f32_e64 s[0:1], s51, v7
	v_ldexp_f32 v21, v21, v29
	v_cmp_nlt_f32_e64 s[14:15], s51, v6
	v_cndmask_b32_e64 v18, 0, v18, s[16:17]
	v_cndmask_b32_e32 v19, 0, v19, vcc
	v_cmp_ngt_f32_e32 vcc, s53, v14
	v_cmp_ngt_f32_e64 s[16:17], s53, v15
	v_cndmask_b32_e64 v14, 0, v20, s[0:1]
	v_cmp_ngt_f32_e64 s[0:1], s53, v7
	v_cndmask_b32_e64 v20, 0, v21, s[14:15]
	v_cmp_ngt_f32_e64 s[14:15], s53, v6
	v_cndmask_b32_e64 v7, v209, v18, s[16:17]
	v_cndmask_b32_e32 v6, v209, v19, vcc
	v_cndmask_b32_e64 v15, v209, v14, s[0:1]
	v_cndmask_b32_e64 v14, v209, v20, s[14:15]
	v_pk_add_f32 v[6:7], v[6:7], 1.0 op_sel_hi:[1,0] neg_lo:[1,0] neg_hi:[1,0]
	v_cmp_lt_f32_e64 vcc, |v13|, 1.0
	v_cmp_lt_f32_e64 s[16:17], |v12|, 1.0
	v_pk_add_f32 v[14:15], v[14:15], 1.0 op_sel_hi:[1,0] neg_lo:[1,0] neg_hi:[1,0]
	v_cmp_lt_f32_e64 s[0:1], |v5|, 1.0
	v_cmp_lt_f32_e64 s[14:15], |v4|, 1.0
	v_cndmask_b32_e64 v6, v6, v16, s[16:17]
	v_cndmask_b32_e32 v7, v7, v17, vcc
	v_cndmask_b32_e64 v8, v14, v8, s[14:15]
	v_cndmask_b32_e64 v9, v15, v9, s[0:1]
	v_bfi_b32 v7, s43, v7, v13
	v_bfi_b32 v6, s43, v6, v12
	v_bfi_b32 v5, s43, v9, v5
	v_bfi_b32 v4, s43, v8, v4
	v_pk_add_f32 v[6:7], v[6:7], 1.0 op_sel_hi:[1,0]
	v_pk_add_f32 v[4:5], v[4:5], 1.0 op_sel_hi:[1,0]
	v_pk_mul_f32 v[6:7], v[10:11], v[6:7]
	v_pk_mul_f32 v[2:3], v[2:3], v[4:5]
	ds_write_b32 v32, v6
	ds_write_b32 v33, v7
	ds_write_b32 v32, v2 offset:4
	ds_write_b32 v33, v3 offset:4
	s_cbranch_scc1 .LBB0_931
	ds_read_b128 v[6:9], v189
	ds_read_b128 v[22:25], v189 offset:16
	ds_read_b128 v[38:41], v189 offset:32
	ds_read_b128 v[54:57], v189 offset:48
	v_lshlrev_b64 v[64:65], 12, v[176:177]
	s_waitcnt lgkmcnt(3)
	s_waitcnt lgkmcnt(2)
	s_waitcnt lgkmcnt(1)
	s_waitcnt lgkmcnt(0)
	v_lshl_or_b32 v4, v7, 7, v137
	v_lshl_or_b32 v0, v6, 7, v174
	v_lshl_or_b32 v12, v9, 7, v137
	v_lshl_or_b32 v8, v8, 7, v174
	v_lshl_or_b32 v20, v23, 7, v137
	v_lshl_or_b32 v16, v22, 7, v174
	v_lshl_or_b32 v28, v25, 7, v137
	v_lshl_or_b32 v24, v24, 7, v174
	v_lshl_or_b32 v36, v39, 7, v137
	v_lshl_or_b32 v32, v38, 7, v174
	v_lshl_or_b32 v44, v41, 7, v137
	v_lshl_or_b32 v40, v40, 7, v174
	v_lshl_or_b32 v52, v55, 7, v137
	v_lshl_or_b32 v48, v54, 7, v174
	v_lshl_or_b32 v60, v57, 7, v137
	v_lshl_or_b32 v56, v56, 7, v174
	v_lshl_add_u64 v[66:67], v[148:149], 0, v[64:65]
	global_load_dwordx4 v[0:3], v0, s[38:39]
	s_nop 0
	global_load_dwordx4 v[4:7], v4, s[38:39]
	s_nop 0
	global_load_dwordx4 v[8:11], v8, s[38:39]
	s_nop 0
	global_load_dwordx4 v[12:15], v12, s[38:39]
	s_nop 0
	global_load_dwordx4 v[16:19], v16, s[38:39]
	s_nop 0
	global_load_dwordx4 v[20:23], v20, s[38:39]
	s_nop 0
	global_load_dwordx4 v[24:27], v24, s[38:39]
	s_nop 0
	global_load_dwordx4 v[28:31], v28, s[38:39]
	s_nop 0
	global_load_dwordx4 v[32:35], v32, s[38:39]
	s_nop 0
	global_load_dwordx4 v[36:39], v36, s[38:39]
	s_nop 0
	global_load_dwordx4 v[40:43], v40, s[38:39]
	s_nop 0
	global_load_dwordx4 v[44:47], v44, s[38:39]
	s_nop 0
	global_load_dwordx4 v[48:51], v48, s[38:39]
	s_nop 0
	global_load_dwordx4 v[52:55], v52, s[38:39]
	s_nop 0
	global_load_dwordx4 v[56:59], v56, s[38:39]
	s_nop 0
	global_load_dwordx4 v[60:63], v60, s[38:39]
	v_lshl_add_u64 v[64:65], v[150:151], 0, v[64:65]
	v_mbcnt_lo_u32_b32 v68, -1, 0
	v_mbcnt_hi_u32_b32 v68, -1, v68
	v_and_b32_e32 v68, 15, v68
	v_add_u32_e32 v68, v68, v176
	v_mov_b32_e32 v69, v139
	v_lshl_add_u64 v[68:69], v[68:69], 3, s[26:27]
	global_load_dword v210, v[66:67], off nt
	global_load_dword v211, v[64:65], off nt
	global_load_dwordx2 v[248:249], v[68:69], off
	s_waitcnt vmcnt(0)
	v_mov_b32_e32 v138, v139
	s_mov_b32 s0, 0
	s_mov_b32 s16, 16
	s_movk_i32 s17, 0x100
	s_mov_b32 s34, 0x40000
	v_mov_b64_e32 v[178:179], v[138:139]
	v_mov_b64_e32 v[180:181], v[138:139]
	s_branch .LBB0_934

.LBB0_934:
	s_add_i32 s15, s17, 0xffffff80
	s_and_b32 s15, s15, 0x780
	v_lshl_add_u32 v76, s15, 2, v189
	ds_read_b128 v[64:67], v76
	s_add_i32 s14, s34, 0xfffc0000
	s_add_i32 s1, s0, 1
	s_and_b32 s14, s14, 0x1e00000
	s_add_u32 s14, s38, s14
	s_waitcnt lgkmcnt(0)
	s_addc_u32 s15, s39, 0
	ds_read_b128 v[68:71], v76 offset:16
	ds_read_b128 v[72:75], v76 offset:32
	ds_read_b128 v[128:131], v76 offset:48
	v_lshl_or_b32 v65, v65, 7, v137
	v_lshl_or_b32 v64, v64, 7, v174
	global_load_dwordx4 v[124:127], v64, s[14:15]
	global_load_dwordx4 v[120:123], v65, s[14:15]
	v_lshl_or_b32 v64, v67, 7, v137
	v_lshl_or_b32 v65, v66, 7, v174
	global_load_dwordx4 v[116:119], v65, s[14:15]
	global_load_dwordx4 v[112:115], v64, s[14:15]
	s_waitcnt lgkmcnt(2)
	v_lshl_or_b32 v64, v69, 7, v137
	v_lshl_or_b32 v65, v68, 7, v174
	global_load_dwordx4 v[108:111], v65, s[14:15]
	global_load_dwordx4 v[104:107], v64, s[14:15]
	v_lshl_or_b32 v64, v71, 7, v137
	v_lshl_or_b32 v65, v70, 7, v174
	global_load_dwordx4 v[100:103], v65, s[14:15]
	global_load_dwordx4 v[96:99], v64, s[14:15]
	s_waitcnt lgkmcnt(1)
	v_lshl_or_b32 v64, v73, 7, v137
	v_lshl_or_b32 v65, v72, 7, v174
	global_load_dwordx4 v[92:95], v65, s[14:15]
	global_load_dwordx4 v[88:91], v64, s[14:15]
	s_and_b32 s59, s1, 15
	v_lshl_or_b32 v64, v75, 7, v137
	v_lshl_or_b32 v65, v74, 7, v174
	s_add_i32 s1, s16, -16
	v_or_b32_e32 v186, s59, v176
	global_load_dwordx4 v[84:87], v65, s[14:15]
	global_load_dwordx4 v[80:83], v64, s[14:15]
	s_waitcnt lgkmcnt(0)
	s_and_b32 s1, s1, 0x780
	v_ashrrev_i32_e32 v187, 31, v186
	v_lshl_or_b32 v64, v129, 7, v137
	v_lshl_or_b32 v65, v128, 7, v174
	v_or_b32_e32 v214, s1, v192
	v_lshlrev_b64 v[128:129], 12, v[186:187]
	global_load_dwordx4 v[76:79], v65, s[14:15]
	global_load_dwordx4 v[72:75], v64, s[14:15]
	v_lshlrev_b32_e32 v64, 7, v131
	v_lshlrev_b32_e32 v65, 7, v130
	v_lshl_add_u64 v[130:131], s[80:81], 0, v[128:129]
	v_lshlrev_b32_e32 v138, 1, v214
	v_lshl_add_u64 v[128:129], s[28:29], 0, v[128:129]
	v_or_b32_e32 v64, v64, v137
	v_or_b32_e32 v65, v65, v174
	v_lshl_add_u64 v[130:131], v[130:131], 0, v[138:139]
	v_lshl_add_u64 v[128:129], v[128:129], 0, v[138:139]
	s_and_b32 s1, s0, 14
	s_waitcnt vmcnt(32)
	v_cvt_pk_f32_fp8_e32 v[224:225], v0
	v_cvt_pk_f32_fp8_sdwa v[226:227], v0 src0_sel:WORD_1
	v_cvt_pk_f32_fp8_e32 v[228:229], v1
	v_cvt_pk_f32_fp8_sdwa v[230:231], v1 src0_sel:WORD_1
	global_load_dwordx4 v[68:71], v65, s[14:15]
	s_nop 0
	global_load_dwordx4 v[64:67], v64, s[14:15]
	global_load_dword v212, v[130:131], off nt
	global_load_dword v213, v[128:129], off nt
	v_lshl_add_u32 v128, s1, 9, v193
	s_waitcnt vmcnt(35)
	v_cvt_pk_f32_fp8_e32 v[240:241], v4
	v_cvt_pk_f32_fp8_sdwa v[242:243], v4 src0_sel:WORD_1
	v_cvt_pk_f32_fp8_e32 v[244:245], v5
	v_cvt_pk_f32_fp8_sdwa v[246:247], v5 src0_sel:WORD_1
	ds_read_b128 v[216:219], v128
	ds_read_b128 v[220:223], v128 offset:16
	ds_read_b128 v[132:135], v128 offset:32
	ds_read_b128 v[128:131], v128 offset:48
	v_cvt_pk_f32_fp8_e32 v[232:233], v2
	s_waitcnt lgkmcnt(3)
	v_pk_fma_f32 v[224:225], v[216:217], v[224:225], 0 op_sel_hi:[0,1,0]
	v_pk_fma_f32 v[226:227], v[216:217], v[226:227], 0 op_sel_hi:[0,1,0]
	v_pk_fma_f32 v[228:229], v[216:217], v[228:229], 0 op_sel_hi:[0,1,0]
	v_pk_fma_f32 v[230:231], v[216:217], v[230:231], 0 op_sel_hi:[0,1,0]
	v_cvt_pk_f32_fp8_sdwa v[234:235], v2 src0_sel:WORD_1
	v_cvt_pk_f32_fp8_e32 v[236:237], v3
	v_cvt_pk_f32_fp8_sdwa v[238:239], v3 src0_sel:WORD_1
	v_pk_fma_f32 v[224:225], v[216:217], v[240:241], v[224:225] op_sel:[1,0,0]
	v_pk_fma_f32 v[226:227], v[216:217], v[242:243], v[226:227] op_sel:[1,0,0]
	v_pk_fma_f32 v[228:229], v[216:217], v[244:245], v[228:229] op_sel:[1,0,0]
	v_pk_fma_f32 v[230:231], v[216:217], v[246:247], v[230:231] op_sel:[1,0,0]
	v_cvt_pk_f32_fp8_e32 v[240:241], v6
	v_cvt_pk_f32_fp8_sdwa v[242:243], v6 src0_sel:WORD_1
	v_cvt_pk_f32_fp8_e32 v[244:245], v7
	v_cvt_pk_f32_fp8_sdwa v[246:247], v7 src0_sel:WORD_1
	v_pk_fma_f32 v[232:233], v[216:217], v[232:233], 0 op_sel_hi:[0,1,0]
	v_pk_fma_f32 v[234:235], v[216:217], v[234:235], 0 op_sel_hi:[0,1,0]
	v_pk_fma_f32 v[236:237], v[216:217], v[236:237], 0 op_sel_hi:[0,1,0]
	v_pk_fma_f32 v[238:239], v[216:217], v[238:239], 0 op_sel_hi:[0,1,0]
	v_pk_fma_f32 v[232:233], v[216:217], v[240:241], v[232:233] op_sel:[1,0,0]
	v_pk_fma_f32 v[234:235], v[216:217], v[242:243], v[234:235] op_sel:[1,0,0]
	v_pk_fma_f32 v[236:237], v[216:217], v[244:245], v[236:237] op_sel:[1,0,0]
	v_pk_fma_f32 v[216:217], v[216:217], v[246:247], v[238:239] op_sel:[1,0,0]
	s_waitcnt vmcnt(34)
	v_cvt_pk_f32_fp8_e32 v[238:239], v8
	v_cvt_pk_f32_fp8_sdwa v[240:241], v8 src0_sel:WORD_1
	v_cvt_pk_f32_fp8_e32 v[242:243], v9
	v_cvt_pk_f32_fp8_sdwa v[244:245], v9 src0_sel:WORD_1
	v_pk_fma_f32 v[224:225], v[218:219], v[238:239], v[224:225] op_sel_hi:[0,1,1]
	v_pk_fma_f32 v[226:227], v[218:219], v[240:241], v[226:227] op_sel_hi:[0,1,1]
	v_pk_fma_f32 v[228:229], v[218:219], v[242:243], v[228:229] op_sel_hi:[0,1,1]
	v_pk_fma_f32 v[230:231], v[218:219], v[244:245], v[230:231] op_sel_hi:[0,1,1]
	v_cvt_pk_f32_fp8_e32 v[238:239], v10
	v_cvt_pk_f32_fp8_sdwa v[240:241], v10 src0_sel:WORD_1
	v_cvt_pk_f32_fp8_e32 v[242:243], v11
	v_cvt_pk_f32_fp8_sdwa v[244:245], v11 src0_sel:WORD_1
	v_pk_fma_f32 v[232:233], v[218:219], v[238:239], v[232:233] op_sel_hi:[0,1,1]
	v_pk_fma_f32 v[234:235], v[218:219], v[240:241], v[234:235] op_sel_hi:[0,1,1]
	v_pk_fma_f32 v[236:237], v[218:219], v[242:243], v[236:237] op_sel_hi:[0,1,1]
	v_pk_fma_f32 v[216:217], v[218:219], v[244:245], v[216:217] op_sel_hi:[0,1,1]
	v_mov_b32_e32 v138, v219
	s_waitcnt vmcnt(33)
	v_cvt_pk_f32_fp8_e32 v[218:219], v12
	v_cvt_pk_f32_fp8_sdwa v[238:239], v12 src0_sel:WORD_1
	v_cvt_pk_f32_fp8_e32 v[240:241], v13
	v_cvt_pk_f32_fp8_sdwa v[242:243], v13 src0_sel:WORD_1
	v_pk_fma_f32 v[218:219], v[138:139], v[218:219], v[224:225] op_sel_hi:[0,1,1]
	v_pk_fma_f32 v[224:225], v[138:139], v[238:239], v[226:227] op_sel_hi:[0,1,1]
	v_pk_fma_f32 v[226:227], v[138:139], v[240:241], v[228:229] op_sel_hi:[0,1,1]
	v_pk_fma_f32 v[228:229], v[138:139], v[242:243], v[230:231] op_sel_hi:[0,1,1]
	v_cvt_pk_f32_fp8_e32 v[230:231], v14
	v_cvt_pk_f32_fp8_sdwa v[238:239], v14 src0_sel:WORD_1
	v_cvt_pk_f32_fp8_e32 v[240:241], v15
	v_cvt_pk_f32_fp8_sdwa v[242:243], v15 src0_sel:WORD_1
	v_pk_fma_f32 v[230:231], v[138:139], v[230:231], v[232:233] op_sel_hi:[0,1,1]
	v_pk_fma_f32 v[232:233], v[138:139], v[238:239], v[234:235] op_sel_hi:[0,1,1]
	v_pk_fma_f32 v[234:235], v[138:139], v[240:241], v[236:237] op_sel_hi:[0,1,1]
	v_pk_fma_f32 v[216:217], v[138:139], v[242:243], v[216:217] op_sel_hi:[0,1,1]
	s_waitcnt vmcnt(32)
	v_cvt_pk_f32_fp8_e32 v[236:237], v16
	v_cvt_pk_f32_fp8_sdwa v[238:239], v16 src0_sel:WORD_1
	v_cvt_pk_f32_fp8_e32 v[240:241], v17
	v_cvt_pk_f32_fp8_sdwa v[242:243], v17 src0_sel:WORD_1
	s_waitcnt lgkmcnt(2)
	v_pk_fma_f32 v[218:219], v[220:221], v[236:237], v[218:219] op_sel_hi:[0,1,1]
	v_pk_fma_f32 v[224:225], v[220:221], v[238:239], v[224:225] op_sel_hi:[0,1,1]
	v_pk_fma_f32 v[226:227], v[220:221], v[240:241], v[226:227] op_sel_hi:[0,1,1]
	v_pk_fma_f32 v[228:229], v[220:221], v[242:243], v[228:229] op_sel_hi:[0,1,1]
	v_cvt_pk_f32_fp8_e32 v[236:237], v18
	v_cvt_pk_f32_fp8_sdwa v[238:239], v18 src0_sel:WORD_1
	v_cvt_pk_f32_fp8_e32 v[240:241], v19
	v_cvt_pk_f32_fp8_sdwa v[242:243], v19 src0_sel:WORD_1
	v_pk_fma_f32 v[230:231], v[220:221], v[236:237], v[230:231] op_sel_hi:[0,1,1]
	v_pk_fma_f32 v[232:233], v[220:221], v[238:239], v[232:233] op_sel_hi:[0,1,1]
	v_pk_fma_f32 v[234:235], v[220:221], v[240:241], v[234:235] op_sel_hi:[0,1,1]
	v_pk_fma_f32 v[216:217], v[220:221], v[242:243], v[216:217] op_sel_hi:[0,1,1]
	s_waitcnt vmcnt(31)
	v_cvt_pk_f32_fp8_e32 v[236:237], v20
	v_cvt_pk_f32_fp8_sdwa v[238:239], v20 src0_sel:WORD_1
	v_cvt_pk_f32_fp8_e32 v[240:241], v21
	v_cvt_pk_f32_fp8_sdwa v[242:243], v21 src0_sel:WORD_1
	v_pk_fma_f32 v[218:219], v[220:221], v[236:237], v[218:219] op_sel:[1,0,0]
	v_pk_fma_f32 v[224:225], v[220:221], v[238:239], v[224:225] op_sel:[1,0,0]
	v_pk_fma_f32 v[226:227], v[220:221], v[240:241], v[226:227] op_sel:[1,0,0]
	v_pk_fma_f32 v[228:229], v[220:221], v[242:243], v[228:229] op_sel:[1,0,0]
	v_cvt_pk_f32_fp8_e32 v[236:237], v22
	v_cvt_pk_f32_fp8_sdwa v[238:239], v22 src0_sel:WORD_1
	v_cvt_pk_f32_fp8_e32 v[240:241], v23
	v_cvt_pk_f32_fp8_sdwa v[242:243], v23 src0_sel:WORD_1
	v_pk_fma_f32 v[230:231], v[220:221], v[236:237], v[230:231] op_sel:[1,0,0]
	v_pk_fma_f32 v[232:233], v[220:221], v[238:239], v[232:233] op_sel:[1,0,0]
	v_pk_fma_f32 v[234:235], v[220:221], v[240:241], v[234:235] op_sel:[1,0,0]
	v_pk_fma_f32 v[216:217], v[220:221], v[242:243], v[216:217] op_sel:[1,0,0]
	s_waitcnt vmcnt(30)
	v_cvt_pk_f32_fp8_e32 v[220:221], v24
	v_cvt_pk_f32_fp8_sdwa v[236:237], v24 src0_sel:WORD_1
	v_cvt_pk_f32_fp8_e32 v[238:239], v25
	v_cvt_pk_f32_fp8_sdwa v[240:241], v25 src0_sel:WORD_1
	v_pk_fma_f32 v[218:219], v[222:223], v[220:221], v[218:219] op_sel_hi:[0,1,1]
	v_pk_fma_f32 v[220:221], v[222:223], v[236:237], v[224:225] op_sel_hi:[0,1,1]
	v_pk_fma_f32 v[224:225], v[222:223], v[238:239], v[226:227] op_sel_hi:[0,1,1]
	v_pk_fma_f32 v[226:227], v[222:223], v[240:241], v[228:229] op_sel_hi:[0,1,1]
	v_cvt_pk_f32_fp8_e32 v[228:229], v26
	v_cvt_pk_f32_fp8_sdwa v[236:237], v26 src0_sel:WORD_1
	v_cvt_pk_f32_fp8_e32 v[238:239], v27
	v_cvt_pk_f32_fp8_sdwa v[240:241], v27 src0_sel:WORD_1
	v_pk_fma_f32 v[228:229], v[222:223], v[228:229], v[230:231] op_sel_hi:[0,1,1]
	v_pk_fma_f32 v[230:231], v[222:223], v[236:237], v[232:233] op_sel_hi:[0,1,1]
	v_pk_fma_f32 v[232:233], v[222:223], v[238:239], v[234:235] op_sel_hi:[0,1,1]
	v_pk_fma_f32 v[216:217], v[222:223], v[240:241], v[216:217] op_sel_hi:[0,1,1]
	v_mov_b32_e32 v138, v223
	s_waitcnt vmcnt(29)
	v_cvt_pk_f32_fp8_e32 v[222:223], v28
	v_cvt_pk_f32_fp8_sdwa v[234:235], v28 src0_sel:WORD_1
	v_cvt_pk_f32_fp8_e32 v[236:237], v29
	v_cvt_pk_f32_fp8_sdwa v[238:239], v29 src0_sel:WORD_1
	v_pk_fma_f32 v[218:219], v[138:139], v[222:223], v[218:219] op_sel_hi:[0,1,1]
	v_pk_fma_f32 v[220:221], v[138:139], v[234:235], v[220:221] op_sel_hi:[0,1,1]
	v_pk_fma_f32 v[222:223], v[138:139], v[236:237], v[224:225] op_sel_hi:[0,1,1]
	v_pk_fma_f32 v[224:225], v[138:139], v[238:239], v[226:227] op_sel_hi:[0,1,1]
	v_cvt_pk_f32_fp8_e32 v[226:227], v30
	v_cvt_pk_f32_fp8_sdwa v[234:235], v30 src0_sel:WORD_1
	v_cvt_pk_f32_fp8_e32 v[236:237], v31
	v_cvt_pk_f32_fp8_sdwa v[238:239], v31 src0_sel:WORD_1
	v_pk_fma_f32 v[226:227], v[138:139], v[226:227], v[228:229] op_sel_hi:[0,1,1]
	v_pk_fma_f32 v[228:229], v[138:139], v[234:235], v[230:231] op_sel_hi:[0,1,1]
	v_pk_fma_f32 v[230:231], v[138:139], v[236:237], v[232:233] op_sel_hi:[0,1,1]
	v_pk_fma_f32 v[216:217], v[138:139], v[238:239], v[216:217] op_sel_hi:[0,1,1]
	s_waitcnt vmcnt(28)
	v_cvt_pk_f32_fp8_e32 v[232:233], v32
	v_cvt_pk_f32_fp8_sdwa v[234:235], v32 src0_sel:WORD_1
	v_cvt_pk_f32_fp8_e32 v[236:237], v33
	v_cvt_pk_f32_fp8_sdwa v[238:239], v33 src0_sel:WORD_1
	s_waitcnt lgkmcnt(1)
	v_pk_fma_f32 v[218:219], v[132:133], v[232:233], v[218:219] op_sel_hi:[0,1,1]
	v_pk_fma_f32 v[220:221], v[132:133], v[234:235], v[220:221] op_sel_hi:[0,1,1]
	v_pk_fma_f32 v[222:223], v[132:133], v[236:237], v[222:223] op_sel_hi:[0,1,1]
	v_pk_fma_f32 v[224:225], v[132:133], v[238:239], v[224:225] op_sel_hi:[0,1,1]
	v_cvt_pk_f32_fp8_e32 v[232:233], v34
	v_cvt_pk_f32_fp8_sdwa v[234:235], v34 src0_sel:WORD_1
	v_cvt_pk_f32_fp8_e32 v[236:237], v35
	v_cvt_pk_f32_fp8_sdwa v[238:239], v35 src0_sel:WORD_1
	v_pk_fma_f32 v[226:227], v[132:133], v[232:233], v[226:227] op_sel_hi:[0,1,1]
	v_pk_fma_f32 v[228:229], v[132:133], v[234:235], v[228:229] op_sel_hi:[0,1,1]
	v_pk_fma_f32 v[230:231], v[132:133], v[236:237], v[230:231] op_sel_hi:[0,1,1]
	v_pk_fma_f32 v[216:217], v[132:133], v[238:239], v[216:217] op_sel_hi:[0,1,1]
	s_waitcnt vmcnt(27)
	v_cvt_pk_f32_fp8_e32 v[232:233], v36
	v_cvt_pk_f32_fp8_sdwa v[234:235], v36 src0_sel:WORD_1
	v_cvt_pk_f32_fp8_e32 v[236:237], v37
	v_cvt_pk_f32_fp8_sdwa v[238:239], v37 src0_sel:WORD_1
	v_pk_fma_f32 v[218:219], v[132:133], v[232:233], v[218:219] op_sel:[1,0,0]
	v_pk_fma_f32 v[220:221], v[132:133], v[234:235], v[220:221] op_sel:[1,0,0]
	v_pk_fma_f32 v[222:223], v[132:133], v[236:237], v[222:223] op_sel:[1,0,0]
	v_pk_fma_f32 v[224:225], v[132:133], v[238:239], v[224:225] op_sel:[1,0,0]
	v_cvt_pk_f32_fp8_e32 v[232:233], v38
	v_cvt_pk_f32_fp8_sdwa v[234:235], v38 src0_sel:WORD_1
	v_cvt_pk_f32_fp8_e32 v[236:237], v39
	v_cvt_pk_f32_fp8_sdwa v[238:239], v39 src0_sel:WORD_1
	v_pk_fma_f32 v[226:227], v[132:133], v[232:233], v[226:227] op_sel:[1,0,0]
	v_pk_fma_f32 v[228:229], v[132:133], v[234:235], v[228:229] op_sel:[1,0,0]
	v_pk_fma_f32 v[230:231], v[132:133], v[236:237], v[230:231] op_sel:[1,0,0]
	v_pk_fma_f32 v[132:133], v[132:133], v[238:239], v[216:217] op_sel:[1,0,0]
	s_waitcnt vmcnt(26)
	v_cvt_pk_f32_fp8_e32 v[216:217], v40
	v_cvt_pk_f32_fp8_sdwa v[232:233], v40 src0_sel:WORD_1
	v_cvt_pk_f32_fp8_e32 v[234:235], v41
	v_cvt_pk_f32_fp8_sdwa v[236:237], v41 src0_sel:WORD_1
	v_pk_fma_f32 v[216:217], v[134:135], v[216:217], v[218:219] op_sel_hi:[0,1,1]
	v_pk_fma_f32 v[218:219], v[134:135], v[232:233], v[220:221] op_sel_hi:[0,1,1]
	v_pk_fma_f32 v[220:221], v[134:135], v[234:235], v[222:223] op_sel_hi:[0,1,1]
	v_pk_fma_f32 v[222:223], v[134:135], v[236:237], v[224:225] op_sel_hi:[0,1,1]
	v_cvt_pk_f32_fp8_e32 v[224:225], v42
	v_cvt_pk_f32_fp8_sdwa v[232:233], v42 src0_sel:WORD_1
	v_cvt_pk_f32_fp8_e32 v[234:235], v43
	v_cvt_pk_f32_fp8_sdwa v[236:237], v43 src0_sel:WORD_1
	v_pk_fma_f32 v[224:225], v[134:135], v[224:225], v[226:227] op_sel_hi:[0,1,1]
	v_pk_fma_f32 v[226:227], v[134:135], v[232:233], v[228:229] op_sel_hi:[0,1,1]
	v_pk_fma_f32 v[228:229], v[134:135], v[234:235], v[230:231] op_sel_hi:[0,1,1]
	v_pk_fma_f32 v[132:133], v[134:135], v[236:237], v[132:133] op_sel_hi:[0,1,1]
	s_waitcnt vmcnt(25)
	v_cvt_pk_f32_fp8_e32 v[230:231], v44
	v_cvt_pk_f32_fp8_sdwa v[232:233], v44 src0_sel:WORD_1
	v_cvt_pk_f32_fp8_e32 v[234:235], v45
	v_cvt_pk_f32_fp8_sdwa v[236:237], v45 src0_sel:WORD_1
	v_mov_b32_e32 v134, v135
	v_pk_fma_f32 v[216:217], v[134:135], v[230:231], v[216:217] op_sel_hi:[0,1,1]
	v_pk_fma_f32 v[218:219], v[134:135], v[232:233], v[218:219] op_sel_hi:[0,1,1]
	v_pk_fma_f32 v[220:221], v[134:135], v[234:235], v[220:221] op_sel_hi:[0,1,1]
	v_pk_fma_f32 v[222:223], v[134:135], v[236:237], v[222:223] op_sel_hi:[0,1,1]
	v_cvt_pk_f32_fp8_e32 v[230:231], v46
	v_cvt_pk_f32_fp8_sdwa v[232:233], v46 src0_sel:WORD_1
	v_cvt_pk_f32_fp8_e32 v[234:235], v47
	v_cvt_pk_f32_fp8_sdwa v[236:237], v47 src0_sel:WORD_1
	v_pk_fma_f32 v[224:225], v[134:135], v[230:231], v[224:225] op_sel_hi:[0,1,1]
	v_pk_fma_f32 v[226:227], v[134:135], v[232:233], v[226:227] op_sel_hi:[0,1,1]
	v_pk_fma_f32 v[228:229], v[134:135], v[234:235], v[228:229] op_sel_hi:[0,1,1]
	v_pk_fma_f32 v[132:133], v[134:135], v[236:237], v[132:133] op_sel_hi:[0,1,1]
	s_waitcnt vmcnt(24)
	v_cvt_pk_f32_fp8_e32 v[134:135], v48
	v_cvt_pk_f32_fp8_sdwa v[230:231], v48 src0_sel:WORD_1
	v_cvt_pk_f32_fp8_e32 v[232:233], v49
	v_cvt_pk_f32_fp8_sdwa v[234:235], v49 src0_sel:WORD_1
	s_waitcnt lgkmcnt(0)
	v_pk_fma_f32 v[134:135], v[128:129], v[134:135], v[216:217] op_sel_hi:[0,1,1]
	v_pk_fma_f32 v[216:217], v[128:129], v[230:231], v[218:219] op_sel_hi:[0,1,1]
	v_pk_fma_f32 v[218:219], v[128:129], v[232:233], v[220:221] op_sel_hi:[0,1,1]
	v_pk_fma_f32 v[220:221], v[128:129], v[234:235], v[222:223] op_sel_hi:[0,1,1]
	v_cvt_pk_f32_fp8_e32 v[222:223], v50
	v_cvt_pk_f32_fp8_sdwa v[230:231], v50 src0_sel:WORD_1
	v_cvt_pk_f32_fp8_e32 v[232:233], v51
	v_cvt_pk_f32_fp8_sdwa v[234:235], v51 src0_sel:WORD_1
	v_pk_fma_f32 v[222:223], v[128:129], v[222:223], v[224:225] op_sel_hi:[0,1,1]
	v_pk_fma_f32 v[224:225], v[128:129], v[230:231], v[226:227] op_sel_hi:[0,1,1]
	v_pk_fma_f32 v[226:227], v[128:129], v[232:233], v[228:229] op_sel_hi:[0,1,1]
	v_pk_fma_f32 v[132:133], v[128:129], v[234:235], v[132:133] op_sel_hi:[0,1,1]
	s_waitcnt vmcnt(23)
	v_cvt_pk_f32_fp8_e32 v[228:229], v52
	v_cvt_pk_f32_fp8_sdwa v[230:231], v52 src0_sel:WORD_1
	v_cvt_pk_f32_fp8_e32 v[232:233], v53
	v_cvt_pk_f32_fp8_sdwa v[234:235], v53 src0_sel:WORD_1
	v_pk_fma_f32 v[134:135], v[128:129], v[228:229], v[134:135] op_sel:[1,0,0]
	v_pk_fma_f32 v[216:217], v[128:129], v[230:231], v[216:217] op_sel:[1,0,0]
	v_pk_fma_f32 v[218:219], v[128:129], v[232:233], v[218:219] op_sel:[1,0,0]
	v_pk_fma_f32 v[220:221], v[128:129], v[234:235], v[220:221] op_sel:[1,0,0]
	v_cvt_pk_f32_fp8_e32 v[228:229], v54
	v_cvt_pk_f32_fp8_sdwa v[230:231], v54 src0_sel:WORD_1
	v_cvt_pk_f32_fp8_e32 v[232:233], v55
	v_cvt_pk_f32_fp8_sdwa v[234:235], v55 src0_sel:WORD_1
	v_pk_fma_f32 v[222:223], v[128:129], v[228:229], v[222:223] op_sel:[1,0,0]
	v_pk_fma_f32 v[224:225], v[128:129], v[230:231], v[224:225] op_sel:[1,0,0]
	v_pk_fma_f32 v[226:227], v[128:129], v[232:233], v[226:227] op_sel:[1,0,0]
	v_pk_fma_f32 v[128:129], v[128:129], v[234:235], v[132:133] op_sel:[1,0,0]
	s_waitcnt vmcnt(22)
	v_cvt_pk_f32_fp8_e32 v[132:133], v56
	v_cvt_pk_f32_fp8_sdwa v[228:229], v56 src0_sel:WORD_1
	v_cvt_pk_f32_fp8_e32 v[230:231], v57
	v_cvt_pk_f32_fp8_sdwa v[232:233], v57 src0_sel:WORD_1
	v_pk_fma_f32 v[132:133], v[130:131], v[132:133], v[134:135] op_sel_hi:[0,1,1]
	v_pk_fma_f32 v[134:135], v[130:131], v[228:229], v[216:217] op_sel_hi:[0,1,1]
	v_pk_fma_f32 v[216:217], v[130:131], v[230:231], v[218:219] op_sel_hi:[0,1,1]
	v_pk_fma_f32 v[218:219], v[130:131], v[232:233], v[220:221] op_sel_hi:[0,1,1]
	v_cvt_pk_f32_fp8_e32 v[220:221], v58
	v_cvt_pk_f32_fp8_sdwa v[228:229], v58 src0_sel:WORD_1
	v_cvt_pk_f32_fp8_e32 v[230:231], v59
	v_cvt_pk_f32_fp8_sdwa v[232:233], v59 src0_sel:WORD_1
	v_pk_fma_f32 v[220:221], v[130:131], v[220:221], v[222:223] op_sel_hi:[0,1,1]
	v_pk_fma_f32 v[222:223], v[130:131], v[228:229], v[224:225] op_sel_hi:[0,1,1]
	s_waitcnt vmcnt(21)
	v_cvt_pk_f32_fp8_sdwa v[228:229], v60 src0_sel:WORD_1
	v_pk_fma_f32 v[224:225], v[130:131], v[230:231], v[226:227] op_sel_hi:[0,1,1]
	v_cvt_pk_f32_fp8_e32 v[226:227], v60
	v_cvt_pk_f32_fp8_e32 v[230:231], v61
	v_pk_fma_f32 v[128:129], v[130:131], v[232:233], v[128:129] op_sel_hi:[0,1,1]
	v_mov_b32_e32 v130, v131
	v_cvt_pk_f32_fp8_sdwa v[232:233], v61 src0_sel:WORD_1
	v_pk_fma_f32 v[134:135], v[130:131], v[228:229], v[134:135] op_sel_hi:[0,1,1]
	v_cvt_pk_f32_fp8_sdwa v[228:229], v62 src0_sel:WORD_1
	v_pk_fma_f32 v[132:133], v[130:131], v[226:227], v[132:133] op_sel_hi:[0,1,1]
	v_pk_fma_f32 v[216:217], v[130:131], v[230:231], v[216:217] op_sel_hi:[0,1,1]
	v_cvt_pk_f32_fp8_e32 v[226:227], v62
	v_cvt_pk_f32_fp8_e32 v[230:231], v63
	v_pk_fma_f32 v[218:219], v[130:131], v[232:233], v[218:219] op_sel_hi:[0,1,1]
	v_cvt_pk_f32_fp8_sdwa v[232:233], v63 src0_sel:WORD_1
	v_pk_fma_f32 v[222:223], v[130:131], v[228:229], v[222:223] op_sel_hi:[0,1,1]
	v_cndmask_b32_e64 v138, v134, v222, s[8:9]
	v_pk_fma_f32 v[220:221], v[130:131], v[226:227], v[220:221] op_sel_hi:[0,1,1]
	v_pk_fma_f32 v[224:225], v[130:131], v[230:231], v[224:225] op_sel_hi:[0,1,1]
	ds_bpermute_b32 v226, v204, v138
	v_cndmask_b32_e64 v138, v135, v223, s[8:9]
	ds_bpermute_b32 v227, v204, v138
	v_cndmask_b32_e64 v138, v216, v224, s[8:9]
	v_pk_fma_f32 v[128:129], v[130:131], v[232:233], v[128:129] op_sel_hi:[0,1,1]
	v_cndmask_b32_e64 v130, v132, v220, s[8:9]
	v_cndmask_b32_e64 v131, v133, v221, s[8:9]
	ds_bpermute_b32 v228, v204, v138
	v_cndmask_b32_e64 v138, v217, v225, s[8:9]
	ds_bpermute_b32 v130, v204, v130
	ds_bpermute_b32 v131, v204, v131
	ds_bpermute_b32 v229, v204, v138
	v_cndmask_b32_e64 v138, v218, v128, s[8:9]
	ds_bpermute_b32 v230, v204, v138
	v_cndmask_b32_e64 v138, v219, v129, s[8:9]
	ds_bpermute_b32 v231, v204, v138
	v_cndmask_b32_e64 v133, v221, v133, s[8:9]
	v_cndmask_b32_e64 v132, v220, v132, s[8:9]
	s_waitcnt lgkmcnt(3)
	v_pk_add_f32 v[130:131], v[132:133], v[130:131]
	v_cndmask_b32_e64 v133, v223, v135, s[8:9]
	v_cndmask_b32_e64 v132, v222, v134, s[8:9]
	v_cndmask_b32_e64 v135, v225, v217, s[8:9]
	v_cndmask_b32_e64 v134, v224, v216, s[8:9]
	s_waitcnt lgkmcnt(2)
	v_pk_add_f32 v[134:135], v[134:135], v[228:229]
	v_cndmask_b32_e64 v129, v129, v219, s[8:9]
	v_cndmask_b32_e64 v128, v128, v218, s[8:9]
	v_pk_add_f32 v[132:133], v[132:133], v[226:227]
	s_waitcnt lgkmcnt(0)
	v_pk_add_f32 v[128:129], v[128:129], v[230:231]
	v_cndmask_b32_e64 v219, v135, v131, s[10:11]
	v_cndmask_b32_e64 v131, v131, v135, s[10:11]
	ds_bpermute_b32 v217, v205, v131
	v_cndmask_b32_e64 v131, v132, v128, s[10:11]
	v_cndmask_b32_e64 v138, v130, v134, s[10:11]
	ds_bpermute_b32 v220, v205, v131
	v_cndmask_b32_e64 v131, v133, v129, s[10:11]
	ds_bpermute_b32 v216, v205, v138
	ds_bpermute_b32 v221, v205, v131
	v_cndmask_b32_e64 v218, v134, v130, s[10:11]
	v_cndmask_b32_e64 v129, v129, v133, s[10:11]
	v_cndmask_b32_e64 v128, v128, v132, s[10:11]
	s_waitcnt lgkmcnt(1)
	v_pk_add_f32 v[130:131], v[218:219], v[216:217]
	s_waitcnt lgkmcnt(0)
	v_pk_add_f32 v[132:133], v[128:129], v[220:221]
	s_cmp_lg_u32 s1, 0
	v_cndmask_b32_e64 v128, v130, v132, s[12:13]
	v_cndmask_b32_e64 v129, v131, v133, s[12:13]
	ds_bpermute_b32 v128, v206, v128
	ds_bpermute_b32 v129, v206, v129
	v_lshlrev_b32_e32 v138, 2, v214
	s_cbranch_scc1 .LBB0_936
	global_load_dwordx2 v[178:179], v138, s[46:47]
	global_load_dwordx2 v[180:181], v138, s[48:49]
.LBB0_936:
	v_cndmask_b32_e64 v131, v133, v131, s[12:13]
	v_cndmask_b32_e64 v130, v132, v130, s[12:13]
	s_waitcnt vmcnt(20)
	v_lshlrev_b32_e32 v132, 16, v210
	v_and_b32_e32 v133, 0xffff0000, v210
	s_waitcnt vmcnt(19)
	v_lshlrev_b32_e32 v134, 16, v211
	v_and_b32_e32 v135, 0xffff0000, v211
	v_readlane_b32 s98, v248, s1
	v_readlane_b32 s99, v249, s1
	v_or_b32_e32 v214, s1, v176
	s_waitcnt lgkmcnt(0)
	v_pk_add_f32 v[128:129], v[130:131], v[128:129]
	ds_bpermute_b32 v128, v250, v128
	ds_bpermute_b32 v129, v250, v129
	v_pk_fma_f32 v[130:131], v[132:133], s[74:75], v[134:135] op_sel_hi:[1,0,1]
	v_ashrrev_i32_e32 v215, 31, v214
	v_pk_add_f32 v[130:131], v[130:131], s[98:99] op_sel_hi:[1,0] neg_lo:[0,1] neg_hi:[0,1]
	s_add_i32 s61, s0, 2
	v_lshlrev_b64 v[214:215], 13, v[214:215]
	v_pk_mul_f32 v[130:131], s[98:99], v[130:131] op_sel:[1,0]
	s_cmpk_gt_u32 s0, 0xfd
	v_lshl_add_u64 v[214:215], s[78:79], 0, v[214:215]
	s_waitcnt vmcnt(0)
	v_pk_fma_f32 v[130:131], v[130:131], v[178:179], v[180:181]
	s_cselect_b64 s[0:1], -1, 0
	v_lshl_add_u64 v[214:215], v[214:215], 0, v[138:139]
	s_waitcnt lgkmcnt(0)
	v_pk_fma_f32 v[128:129], v[130:131], s[74:75], v[128:129] op_sel_hi:[1,0,1]
	s_and_b64 vcc, exec, s[0:1]
	global_store_dwordx2 v[214:215], v[128:129], off nt
	s_cbranch_vccnz .LBB0_933
	s_and_b32 s15, s17, 0x700
	v_lshl_add_u32 v0, s15, 2, v189
	ds_read_b128 v[6:9], v0
	ds_read_b128 v[22:25], v0 offset:16
	ds_read_b128 v[38:41], v0 offset:32
	ds_read_b128 v[54:57], v0 offset:48
	s_and_b32 s14, s34, 0x3e00000
	s_add_u32 s14, s38, s14
	s_waitcnt lgkmcnt(2)
	s_waitcnt lgkmcnt(1)
	s_waitcnt lgkmcnt(0)
	s_addc_u32 s15, s39, 0
	v_lshl_or_b32 v4, v7, 7, v137
	v_lshl_or_b32 v0, v6, 7, v174
	v_lshl_or_b32 v12, v9, 7, v137
	v_lshl_or_b32 v8, v8, 7, v174
	v_lshl_or_b32 v20, v23, 7, v137
	v_lshl_or_b32 v16, v22, 7, v174
	v_lshl_or_b32 v28, v25, 7, v137
	v_lshl_or_b32 v24, v24, 7, v174
	v_lshl_or_b32 v36, v39, 7, v137
	v_lshl_or_b32 v32, v38, 7, v174
	v_lshl_or_b32 v44, v41, 7, v137
	v_lshl_or_b32 v40, v40, 7, v174
	v_lshl_or_b32 v52, v55, 7, v137
	v_lshl_or_b32 v48, v54, 7, v174
	v_lshl_or_b32 v60, v57, 7, v137
	v_lshl_or_b32 v56, v56, 7, v174
	v_and_or_b32 v128, s61, 14, v176
	global_load_dwordx4 v[0:3], v0, s[14:15]
	s_nop 0
	global_load_dwordx4 v[4:7], v4, s[14:15]
	s_nop 0
	global_load_dwordx4 v[8:11], v8, s[14:15]
	s_nop 0
	global_load_dwordx4 v[12:15], v12, s[14:15]
	s_nop 0
	global_load_dwordx4 v[16:19], v16, s[14:15]
	s_nop 0
	global_load_dwordx4 v[20:23], v20, s[14:15]
	s_nop 0
	global_load_dwordx4 v[24:27], v24, s[14:15]
	s_nop 0
	global_load_dwordx4 v[28:31], v28, s[14:15]
	s_nop 0
	global_load_dwordx4 v[32:35], v32, s[14:15]
	s_nop 0
	global_load_dwordx4 v[36:39], v36, s[14:15]
	s_nop 0
	global_load_dwordx4 v[40:43], v40, s[14:15]
	s_nop 0
	global_load_dwordx4 v[44:47], v44, s[14:15]
	s_nop 0
	global_load_dwordx4 v[48:51], v48, s[14:15]
	s_nop 0
	global_load_dwordx4 v[52:55], v52, s[14:15]
	s_nop 0
	global_load_dwordx4 v[56:59], v56, s[14:15]
	s_nop 0
	global_load_dwordx4 v[60:63], v60, s[14:15]
	s_and_b32 s14, s16, 0xf80
	v_ashrrev_i32_e32 v129, 31, v128
	v_or_b32_e32 v134, s14, v192
	v_lshlrev_b64 v[130:131], 12, v[128:129]
	v_lshl_add_u64 v[132:133], s[80:81], 0, v[130:131]
	v_lshlrev_b32_e32 v134, 1, v134
	v_mov_b32_e32 v135, v139
	v_lshl_add_u64 v[132:133], v[132:133], 0, v[134:135]
	v_lshl_add_u64 v[130:131], s[28:29], 0, v[130:131]
	v_lshl_add_u64 v[130:131], v[130:131], 0, v[134:135]
	global_load_dword v210, v[132:133], off nt
	global_load_dword v211, v[130:131], off nt
	s_branch .LBB0_933

	.amdhsa_kernel _Z4mega6Paramsii
		.amdhsa_group_segment_fixed_size 16400
		.amdhsa_private_segment_fixed_size 0
		.amdhsa_kernarg_size 416
		.amdhsa_user_sgpr_count 2
		.amdhsa_user_sgpr_dispatch_ptr 0
		.amdhsa_user_sgpr_queue_ptr 0
		.amdhsa_user_sgpr_kernarg_segment_ptr 1
		.amdhsa_user_sgpr_dispatch_id 0
		.amdhsa_user_sgpr_kernarg_preload_length 0
		.amdhsa_user_sgpr_kernarg_preload_offset 0
		.amdhsa_user_sgpr_private_segment_size 0
		.amdhsa_uses_dynamic_stack 0
		.amdhsa_enable_private_segment 0
		.amdhsa_system_sgpr_workgroup_id_x 1
		.amdhsa_system_sgpr_workgroup_id_y 0
		.amdhsa_system_sgpr_workgroup_id_z 0
		.amdhsa_system_sgpr_workgroup_info 0
		.amdhsa_system_vgpr_workitem_id 2
		.amdhsa_next_free_vgpr 256
		.amdhsa_next_free_sgpr 100
		.amdhsa_accum_offset 256
		.amdhsa_reserve_vcc 1
		.amdhsa_float_round_mode_32 0
		.amdhsa_float_round_mode_16_64 0
		.amdhsa_float_denorm_mode_32 3
		.amdhsa_float_denorm_mode_16_64 3
		.amdhsa_dx10_clamp 1
		.amdhsa_ieee_mode 1
		.amdhsa_fp16_overflow 0
		.amdhsa_tg_split 0
		.amdhsa_exception_fp_ieee_invalid_op 0
		.amdhsa_exception_fp_denorm_src 0
		.amdhsa_exception_fp_ieee_div_zero 0
		.amdhsa_exception_fp_ieee_overflow 0
		.amdhsa_exception_fp_ieee_underflow 0
		.amdhsa_exception_fp_ieee_inexact 0
		.amdhsa_exception_int_div_zero 0
	.end_amdhsa_kernel

amdhsa.kernels:
  - .agpr_count:     0
    .args:
      - .offset:         0
        .size:           152
        .value_kind:     by_value
      - .offset:         152
        .size:           4
        .value_kind:     by_value
      - .offset:         156
        .size:           4
        .value_kind:     by_value
      - .offset:         160
        .size:           4
        .value_kind:     hidden_block_count_x
      - .offset:         164
        .size:           4
        .value_kind:     hidden_block_count_y
      - .offset:         168
        .size:           4
        .value_kind:     hidden_block_count_z
      - .offset:         172
        .size:           2
        .value_kind:     hidden_group_size_x
      - .offset:         174
        .size:           2
        .value_kind:     hidden_group_size_y
      - .offset:         176
        .size:           2
        .value_kind:     hidden_group_size_z
      - .offset:         178
        .size:           2
        .value_kind:     hidden_remainder_x
      - .offset:         180
        .size:           2
        .value_kind:     hidden_remainder_y
      - .offset:         182
        .size:           2
        .value_kind:     hidden_remainder_z
      - .offset:         200
        .size:           8
        .value_kind:     hidden_global_offset_x
      - .offset:         208
        .size:           8
        .value_kind:     hidden_global_offset_y
      - .offset:         216
        .size:           8
        .value_kind:     hidden_global_offset_z
      - .offset:         224
        .size:           2
        .value_kind:     hidden_grid_dims
      - .offset:         248
        .size:           8
        .value_kind:     hidden_multigrid_sync_arg
      - .offset:         280
        .size:           4
        .value_kind:     hidden_dynamic_lds_size
    .group_segment_fixed_size: 16400
    .kernarg_segment_align: 8
    .kernarg_segment_size: 416
    .language:       OpenCL C
    .language_version:
      - 2
      - 0
    .max_flat_workgroup_size: 512
    .name:           _Z4mega6Paramsii
    .private_segment_fixed_size: 0
    .sgpr_count:     106
    .sgpr_spill_count: 13
    .symbol:         _Z4mega6Paramsii.kd
    .uniform_work_group_size: 1
    .uses_dynamic_stack: false
    .vgpr_count:     256
    .vgpr_spill_count: 0
    .wavefront_size: 64
